# RWKV-7 stage-2 recurrence: waves 4..7 (shadow copies whose results are unused) no longer load or compute, they only keep the barrier sequence; on top of v40
# speedup vs baseline: 1.0142x; 1.0105x over previous
.LBB0_223:
	s_lshr_b32 s4, s3, 6
	s_bfe_u32 s5, s3, 0x20006
	s_lshl_b32 s3, s4, 4
	s_lshl_b32 s14, s14, 1
	s_bfe_u32 s4, s4, 0x10001
	s_or_b32 s4, s4, s14
	s_lshl_b32 s2, s2, 2
	v_add_lshl_u32 v10, v12, s3, 1
	s_lshl_b32 s3, s4, 9
	s_and_b32 s2, s2, 4
	s_lshl_b32 s14, s4, 6
	v_and_b32_e32 v10, 48, v10
	v_lshlrev_b32_e32 v100, 3, v234
	s_or_b32 s2, s3, s2
	v_or3_b32 v9, v10, s14, v9
	v_or_b32_e32 v10, s2, v100
	v_lshlrev_b32_e32 v190, 1, v10
	v_lshl_add_u64 v[10:11], s[12:13], 0, v[190:191]
	s_lshl_b64 s[40:41], s[36:37], 13
	s_waitcnt vmcnt(4)
	v_lshl_add_u64 v[84:85], v[10:11], 0, s[40:41]
	s_mov_b32 s2, 0x1ac01000
	v_add_co_u32_e32 v10, vcc, s2, v84
	s_waitcnt lgkmcnt(0)
	s_barrier
	s_cmp_eq_u64 s[18:19], 0
	s_cbranch_scc1 .Lpf_d
	s_nop 0
	v_addc_co_u32_e32 v11, vcc, 0, v85, vcc
	global_load_dwordx2 v[70:71], v[10:11], off
	s_lshl_b32 s26, s5, 11
	s_add_u32 s2, s12, s40
	s_addc_u32 s3, s13, s41
	s_add_u32 s36, s2, 0x1a401000
	s_addc_u32 s37, s3, 0
	s_add_u32 s2, s36, s26
	s_addc_u32 s3, s37, 0
	v_lshlrev_b32_e32 v190, 4, v234
	global_load_dwordx4 v[10:13], v190, s[2:3]
	global_load_dwordx4 v[74:77], v190, s[2:3] offset:1024
	v_lshl_add_u64 v[96:97], s[2:3], 0, v[190:191]
	s_mov_b32 s2, 0x1ac11000
	v_add_co_u32_e32 v14, vcc, s2, v84
	s_mov_b64 s[2:3], 0x10000
	s_nop 0
	v_addc_co_u32_e32 v15, vcc, 0, v85, vcc
	global_load_dwordx2 v[98:99], v[14:15], off
	v_lshl_add_u64 v[14:15], v[96:97], 0, s[2:3]
	s_mov_b32 s2, 0x10000
	v_add_co_u32_e32 v16, vcc, s2, v96
	s_mov_b32 s2, 0x1ac21000
	s_nop 0
	v_addc_co_u32_e32 v17, vcc, 0, v97, vcc
	global_load_dwordx4 v[34:37], v[16:17], off
	global_load_dwordx4 v[66:69], v[14:15], off offset:1024
	v_add_co_u32_e32 v14, vcc, s2, v84
	s_mov_b64 s[2:3], 0x20000
	s_nop 0
	v_addc_co_u32_e32 v15, vcc, 0, v85, vcc
	global_load_dwordx2 v[86:87], v[14:15], off
	v_lshl_add_u64 v[14:15], v[96:97], 0, s[2:3]
	s_mov_b32 s2, 0x20000
	v_add_co_u32_e32 v16, vcc, s2, v96
	s_mov_b32 s2, 0x1ac31000
	s_nop 0
	v_addc_co_u32_e32 v17, vcc, 0, v97, vcc
	global_load_dwordx4 v[22:25], v[16:17], off
	global_load_dwordx4 v[50:53], v[14:15], off offset:1024
	v_add_co_u32_e32 v14, vcc, s2, v84
	s_mov_b64 s[2:3], 0x30000
	s_nop 0
	v_addc_co_u32_e32 v15, vcc, 0, v85, vcc
	global_load_dwordx2 v[88:89], v[14:15], off
	v_lshl_add_u64 v[14:15], v[96:97], 0, s[2:3]
	s_mov_b32 s2, 0x30000
	v_add_co_u32_e32 v16, vcc, s2, v96
	s_mov_b32 s2, 0x1ac41000
	s_nop 0
	v_addc_co_u32_e32 v17, vcc, 0, v97, vcc
	global_load_dwordx4 v[38:41], v[16:17], off
	global_load_dwordx4 v[62:65], v[14:15], off offset:1024
	v_add_co_u32_e32 v14, vcc, s2, v84
	s_mov_b64 s[2:3], 0x40000
	s_nop 0
	v_addc_co_u32_e32 v15, vcc, 0, v85, vcc
	global_load_dwordx2 v[90:91], v[14:15], off
	v_lshl_add_u64 v[14:15], v[96:97], 0, s[2:3]
	s_mov_b32 s2, 0x40000
	v_add_co_u32_e32 v16, vcc, s2, v96
	s_mov_b32 s2, 0x1ac51000
	s_nop 0
	v_addc_co_u32_e32 v17, vcc, 0, v97, vcc
	global_load_dwordx4 v[26:29], v[16:17], off
	global_load_dwordx4 v[54:57], v[14:15], off offset:1024
	v_add_co_u32_e32 v14, vcc, s2, v84
	s_mov_b64 s[2:3], 0x50000
	s_nop 0
	v_addc_co_u32_e32 v15, vcc, 0, v85, vcc
	global_load_dwordx2 v[92:93], v[14:15], off
	v_lshl_add_u64 v[14:15], v[96:97], 0, s[2:3]
	s_mov_b32 s2, 0x50000
	v_add_co_u32_e32 v16, vcc, s2, v96
	s_mov_b32 s2, 0x1ac61000
	s_nop 0
	v_addc_co_u32_e32 v17, vcc, 0, v97, vcc
	global_load_dwordx4 v[42:45], v[16:17], off
	global_load_dwordx4 v[58:61], v[14:15], off offset:1024
	v_add_co_u32_e32 v14, vcc, s2, v84
	s_mov_b64 s[2:3], 0x60000
	s_nop 0
	v_addc_co_u32_e32 v15, vcc, 0, v85, vcc
	global_load_dwordx2 v[80:81], v[14:15], off
	v_lshl_add_u64 v[14:15], v[96:97], 0, s[2:3]
	s_mov_b32 s2, 0x60000
	v_add_co_u32_e32 v16, vcc, s2, v96
	s_mov_b32 s2, 0x1ac71000
	s_nop 0
	v_addc_co_u32_e32 v17, vcc, 0, v97, vcc
	global_load_dwordx4 v[30:33], v[16:17], off
	global_load_dwordx4 v[46:49], v[14:15], off offset:1024
	v_add_co_u32_e32 v14, vcc, s2, v84
	s_mov_b64 s[2:3], 0x70000
	s_nop 0
	v_addc_co_u32_e32 v15, vcc, 0, v85, vcc
	v_lshl_add_u64 v[18:19], v[96:97], 0, s[2:3]
	s_mov_b32 s2, 0x70000
	global_load_dwordx2 v[78:79], v[14:15], off
	v_add_co_u32_e32 v14, vcc, s2, v96
	v_add_u32_e32 v72, 0, v8
	s_lshl_b32 s2, s5, 5
	v_lshl_or_b32 v94, v9, 3, v6
	v_add3_u32 v114, v72, s2, v7
	s_waitcnt vmcnt(21)
	v_lshlrev_b32_e32 v6, 16, v70
	v_and_b32_e32 v7, 0xffff0000, v70
	v_and_b32_e32 v70, 48, v235
	v_addc_co_u32_e32 v15, vcc, 0, v97, vcc
	v_add_u32_e32 v115, v72, v70
	global_load_dwordx4 v[14:17], v[14:15], off
	s_nop 0
	global_load_dwordx4 v[18:21], v[18:19], off offset:1024
	v_lshlrev_b32_e32 v8, 16, v71
	v_and_b32_e32 v9, 0xffff0000, v71
	ds_read_b128 v[70:73], v115
	s_mov_b64 s[2:3], 0x80000
	s_waitcnt vmcnt(22) lgkmcnt(0)
	v_mfma_f32_16x16x32_bf16 v[70:73], v[10:13], v[70:73], v[6:9]
	s_nop 2
	ds_read_b128 v[6:9], v115 offset:64
	v_lshl_add_u64 v[10:11], v[96:97], 0, s[2:3]
	v_mov_b32_e32 v95, v191
	s_waitcnt vmcnt(21) lgkmcnt(0)
	v_mfma_f32_16x16x32_bf16 v[74:77], v[74:77], v[6:9], 0
	v_add_co_u32_e32 v6, vcc, 0x1ac81000, v84
	s_nop 1
	v_addc_co_u32_e32 v7, vcc, 0, v85, vcc
	global_load_dwordx2 v[82:83], v[6:7], off
	v_add_co_u32_e32 v6, vcc, 0x80000, v96
	v_cndmask_b32_e64 v96, 0, 1, s[18:19]
	s_nop 0
	v_addc_co_u32_e32 v7, vcc, 0, v97, vcc
	global_load_dwordx4 v[6:9], v[6:7], off
	s_nop 0
	global_load_dwordx4 v[10:13], v[10:11], off offset:1024
	v_cmp_ne_u32_e64 s[38:39], 1, v96
	s_andn2_b64 vcc, exec, s[18:19]
	s_cbranch_vccnz .LBB0_225
	s_add_u32 s2, s1, s40
	v_pk_add_f32 v[72:73], v[72:73], v[76:77]
	v_pk_add_f32 v[70:71], v[70:71], v[74:75]
	s_addc_u32 s3, s23, s41
	v_cvt_pk_bf16_f32 v70, v70, v71
	v_cvt_pk_bf16_f32 v71, v72, v73
	v_lshl_add_u64 v[72:73], v[94:95], 1, s[2:3]
	v_add_co_u32_e32 v72, vcc, 0x10000, v72
	ds_write_b64 v114, v[70:71] offset:2304
	s_nop 0
	v_addc_co_u32_e32 v73, vcc, 0, v73, vcc
	global_store_dwordx2 v[72:73], v[70:71], off

.Lpf_d:
	s_mov_b32 s23, 0
.Lpf_d_half:
	s_mov_b32 s21, 63
.Lpf_d_step:
	s_barrier
	s_sub_i32 s21, s21, 1
	s_cmp_lg_u32 s21, 0
	s_cbranch_scc1 .Lpf_d_step
	s_cmp_lg_u32 s23, 0
	s_cbranch_scc1 .Lpf_d_done
	s_mov_b32 s23, 1
	s_barrier
	s_branch .Lpf_d_half
.Lpf_d_done:
	s_branch .LBB0_480
.LBB0_484:
	s_mov_b64 s[18:19], 0
	s_cbranch_execz .LBB0_483
